# RG-LRU chunk loop: counted vmcnt(16) at step 5 so the y-branch load is awaited without draining the next chunk's 16 prefetch loads
# speedup vs baseline: 1.0009x; 1.0009x over previous
; __device__ __forceinline__ void unit(const Args& A, LAS unsigned char* lds, int un) {
;     ...
;         __syncthreads();
; #pragma unroll
;         for (int t2 = 0; t2 < 2; ++t2) { float hin = hc[t2], mine = 0.f;
; #pragma unroll
;             for (int w = 0; w < 8; ++w) { const float P = AS[w * 32 + 16 * t2 + fr], H = AS[256 + w * 32 + 16 * t2 + fr]; if (w == wid) mine = hin; hin = P * hin + H; }
;             hc[t2] = hin;
;             const float cl = Pe[t2] * mine + He[t2];
; #pragma unroll
;             for (int rg = 0; rg < 4; ++rg) US[(16 * wid + 4 * fq + rg) * 32 + 16 * t2 + fr] = Hl[t2][rg] + Pl[t2][rg] * cl; }
.LBB0_238:
	s_or_b64 exec, exec, s[80:81]
	s_waitcnt lgkmcnt(0)
	s_barrier
	ds_read2_b32 v[124:125], v182 offset1:16
	v_add_u32_e32 v121, 0x400, v182
	ds_read2_b32 v[126:127], v121 offset1:16
	ds_read2_b32 v[128:129], v182 offset0:32 offset1:48
	ds_read2_b32 v[130:131], v121 offset0:32 offset1:48
	ds_read2_b32 v[140:141], v182 offset0:64 offset1:80
	ds_read2_b32 v[142:143], v121 offset0:64 offset1:80
	v_cndmask_b32_e64 v139, 0, v2, s[18:19]
	s_waitcnt lgkmcnt(4)
	v_fma_f32 v2, v2, v124, v126
	ds_read2_b32 v[208:209], v182 offset0:96 offset1:112
	ds_read2_b32 v[210:211], v121 offset0:96 offset1:112
	ds_read2_b32 v[212:213], v182 offset0:128 offset1:144
	ds_read2_b32 v[214:215], v121 offset0:128 offset1:144
	ds_read2_b32 v[216:217], v182 offset0:160 offset1:176
	ds_read2_b32 v[218:219], v121 offset0:160 offset1:176
	ds_read2_b32 v[220:221], v182 offset0:192 offset1:208
	ds_read2_b32 v[222:223], v121 offset0:192 offset1:208
	ds_read2_b32 v[224:225], v182 offset0:224 offset1:240
	ds_read2_b32 v[226:227], v121 offset0:224 offset1:240
	v_cndmask_b32_e64 v121, 0, v3, s[18:19]
	v_fmac_f32_e32 v127, v3, v125
	v_cndmask_b32_e64 v124, v139, v2, s[20:21]
	s_waitcnt lgkmcnt(12)
	v_fma_f32 v2, v2, v128, v130
	v_cndmask_b32_e64 v3, v121, v127, s[20:21]
	v_fmac_f32_e32 v131, v127, v129
	v_cndmask_b32_e64 v124, v124, v2, s[22:23]
	s_waitcnt lgkmcnt(11)
	v_mul_f32_e32 v2, v2, v140
	v_cndmask_b32_e64 v121, v3, v131, s[22:23]
	v_mul_f32_e32 v3, v131, v141
	s_waitcnt lgkmcnt(10)
	v_pk_add_f32 v[2:3], v[2:3], v[142:143]
	s_add_u32 s78, s78, 0x140000
	v_cndmask_b32_e64 v126, v124, v2, s[24:25]
	s_waitcnt lgkmcnt(8)
	v_pk_fma_f32 v[124:125], v[2:3], v[208:209], v[210:211]
	s_addc_u32 s79, s79, 0
	v_cndmask_b32_e64 v2, v126, v124, s[26:27]
	s_waitcnt lgkmcnt(6)
	v_pk_fma_f32 v[126:127], v[124:125], v[212:213], v[214:215]
	s_cmp_lg_u32 s78, 0x1400000
	v_cndmask_b32_e64 v2, v2, v126, s[28:29]
	s_waitcnt lgkmcnt(4)
	v_pk_fma_f32 v[128:129], v[126:127], v[216:217], v[218:219]
	s_nop 0
	v_cndmask_b32_e64 v2, v2, v128, s[30:31]
	s_waitcnt lgkmcnt(2)
	v_pk_fma_f32 v[130:131], v[128:129], v[220:221], v[222:223]
	s_nop 0
	v_cndmask_b32_e64 v2, v2, v130, s[34:35]
	v_fmac_f32_e32 v122, v123, v2
	v_cndmask_b32_e64 v2, v121, v3, s[24:25]
	v_cndmask_b32_e64 v2, v2, v125, s[26:27]
	v_cndmask_b32_e64 v2, v2, v127, s[28:29]
	v_cndmask_b32_e64 v2, v2, v129, s[30:31]
	v_cndmask_b32_e64 v121, v2, v131, s[34:35]
	v_fmac_f32_e32 v118, v119, v121
	v_fmac_f32_e32 v112, v120, v118
	s_cbranch_scc1 .Llru_w16
	s_waitcnt vmcnt(0)
	s_branch .Llru_wdone
.Llru_w16:
	s_waitcnt vmcnt(16)
; #define LAS __attribute__((address_space(3)))
; __device__ __forceinline__ unsigned pk2(float lo, float hi) { return f2bf(lo) | (f2bf(hi) << 16); }
; __device__ __forceinline__ float bflo(unsigned w) { return __uint_as_float(w << 16); }
; __device__ __forceinline__ float bfhi(unsigned w) { return __uint_as_float(w & 0xffff0000u); }
; __device__ __forceinline__ float sigmoidf_(float x) { return __builtin_amdgcn_rcpf(1.0f + __builtin_amdgcn_exp2f(-LOG2E * x)); }
; __device__ __forceinline__ void unit(const Args& A, LAS unsigned char* lds, int un) {
;     ...
;             for (int rg = 0; rg < 4; ++rg) US[(16 * wid + 4 * fq + rg) * 32 + 16 * t2 + fr] = Hl[t2][rg] + Pl[t2][rg] * cl; }
;         __syncthreads();
;         { const int tok = tid >> 2, c8 = (tid & 3) * 8; const size_t rowi = (size_t)b * SEQ + t0 + tok;
;           const LAS f32x4* hp = (const LAS f32x4*)(US + tok * 32 + c8); const f32x4 h0 = hp[0], h1 = hp[1];
;           float y[8] = {bflo(yw.x), bfhi(yw.x), bflo(yw.y), bfhi(yw.y), bflo(yw.z), bfhi(yw.z), bflo(yw.w), bfhi(yw.w)};
;           float hv[8] = {h0[0], h0[1], h0[2], h0[3], h1[0], h1[1], h1[2], h1[3]}; float o[8];
; #pragma unroll
;           for (int j = 0; j < 8; ++j) { const float z = 0.7978845608028654f * (y[j] + 0.044715f * y[j] * y[j] * y[j]); o[j] = hv[j] * y[j] * sigmoidf_(2.0f * z); }
;           u32x4 w; w.x = pk2(o[0], o[1]); w.y = pk2(o[2], o[3]); w.z = pk2(o[4], o[5]); w.w = pk2(o[6], o[7]);
;           *(u32x4*)(A.merged + rowi * D + n * 128 + 32 * qd + c8) = w; }
.Llru_wdone:
	v_lshlrev_b32_e32 v120, 16, v108
	v_fmac_f32_e32 v116, v1, v118
	v_mul_f32_e32 v1, 0x3d372713, v120
	v_fmac_f32_e32 v132, v168, v122
	v_fmac_f32_e32 v136, v133, v122
	v_fmac_f32_e32 v134, v137, v122
	v_fmac_f32_e32 v135, v138, v122
	v_mul_f32_e32 v1, v1, v120
	v_mov_b32_e32 v122, v120
	v_and_b32_e32 v108, 0xffff0000, v108
	v_fmac_f32_e32 v122, v1, v122
	v_mul_f32_e32 v1, 0x3f4c422a, v122
	v_mul_f32_e32 v122, 0x3d372713, v108
	v_mul_f32_e32 v122, v122, v108
	v_mov_b32_e32 v123, v108
	v_fmac_f32_e32 v123, v122, v123
	v_add_f32_e32 v1, v1, v1
	v_mul_f32_e32 v122, 0x3f4c422a, v123
	v_mul_f32_e32 v1, 0xbfb8aa3b, v1
	v_add_f32_e32 v122, v122, v122
	v_exp_f32_e32 v1, v1
	v_mul_f32_e32 v122, 0xbfb8aa3b, v122
	v_exp_f32_e32 v123, v122
	v_fmac_f32_e32 v114, v113, v118
	v_fmac_f32_e32 v115, v117, v118
	ds_write2_b32 v205, v132, v112 offset1:16
	ds_write2_b32 v205, v136, v116 offset0:32 offset1:48
	ds_write2_b32 v205, v134, v114 offset0:64 offset1:80
	ds_write2_b32 v205, v135, v115 offset0:96 offset1:112
	s_waitcnt lgkmcnt(0)
	s_barrier
	ds_read_b128 v[112:115], v184
	ds_read_b128 v[116:119], v184 offset:16
	v_add_f32_e32 v1, 1.0, v1
	v_lshlrev_b32_e32 v121, 16, v109
	v_rcp_f32_e32 v122, v1
	v_add_f32_e32 v1, 1.0, v123
	v_and_b32_e32 v109, 0xffff0000, v109
	v_rcp_f32_e32 v124, v1
	v_mul_f32_e32 v1, 0x3d372713, v121
	v_mul_f32_e32 v1, v1, v121
	v_mov_b32_e32 v123, v121
	s_waitcnt lgkmcnt(1)
	v_mov_b32_e32 v126, v112
	v_mul_f32_e32 v112, 0x3d372713, v109
	v_fmac_f32_e32 v123, v1, v123
	v_mov_b32_e32 v127, v114
	v_mul_f32_e32 v112, v112, v109
	v_mov_b32_e32 v114, v109
	v_mul_f32_e32 v1, 0x3f4c422a, v123
	v_fmac_f32_e32 v114, v112, v114
	v_add_f32_e32 v1, v1, v1
	v_mul_f32_e32 v112, 0x3f4c422a, v114
	v_mul_f32_e32 v1, 0xbfb8aa3b, v1
	v_add_f32_e32 v112, v112, v112
	v_exp_f32_e32 v1, v1
	v_mul_f32_e32 v112, 0xbfb8aa3b, v112
	v_exp_f32_e32 v112, v112
	v_mov_b32_e32 v114, v113
	v_add_f32_e32 v1, 1.0, v1
	v_rcp_f32_e32 v123, v1
	v_add_f32_e32 v1, 1.0, v112
	v_lshlrev_b32_e32 v112, 16, v110
	v_rcp_f32_e32 v125, v1
	v_mul_f32_e32 v1, 0x3d372713, v112
	v_pk_mul_f32 v[108:109], v[114:115], v[108:109]
	v_mul_f32_e32 v1, v1, v112
	v_mov_b32_e32 v114, v112
	v_and_b32_e32 v110, 0xffff0000, v110
	v_fmac_f32_e32 v114, v1, v114
	v_mul_f32_e32 v1, 0x3f4c422a, v114
	v_mul_f32_e32 v114, 0x3d372713, v110
	v_mul_f32_e32 v114, v114, v110
	v_mov_b32_e32 v115, v110
	v_fmac_f32_e32 v115, v114, v115
	v_add_f32_e32 v1, v1, v1
	v_mul_f32_e32 v114, 0x3f4c422a, v115
	v_mul_f32_e32 v1, 0xbfb8aa3b, v1
	v_add_f32_e32 v114, v114, v114
	v_exp_f32_e32 v1, v1
	v_mul_f32_e32 v114, 0xbfb8aa3b, v114
	v_exp_f32_e32 v115, v114
	v_pk_mul_f32 v[120:121], v[126:127], v[120:121]
	v_add_f32_e32 v1, 1.0, v1
	v_lshlrev_b32_e32 v113, 16, v111
	v_rcp_f32_e32 v114, v1
	v_add_f32_e32 v1, 1.0, v115
	v_pk_mul_f32 v[120:121], v[122:123], v[120:121]
	v_rcp_f32_e32 v122, v1
	v_mul_f32_e32 v1, 0x3d372713, v113
	v_mul_f32_e32 v1, v1, v113
	v_mov_b32_e32 v115, v113
	v_and_b32_e32 v111, 0xffff0000, v111
	v_fmac_f32_e32 v115, v1, v115
	v_mul_f32_e32 v1, 0x3f4c422a, v115
	v_mul_f32_e32 v115, 0x3d372713, v111
	v_pk_mul_f32 v[108:109], v[124:125], v[108:109]
	s_waitcnt lgkmcnt(0)
	v_mov_b32_e32 v124, v116
	v_mul_f32_e32 v115, v115, v111
	v_mov_b32_e32 v116, v111
	v_fmac_f32_e32 v116, v115, v116
	v_add_f32_e32 v1, v1, v1
	v_mul_f32_e32 v115, 0x3f4c422a, v116
	v_mul_f32_e32 v1, 0xbfb8aa3b, v1
	v_add_f32_e32 v115, v115, v115
	v_exp_f32_e32 v1, v1
	v_mul_f32_e32 v115, 0xbfb8aa3b, v115
	v_exp_f32_e32 v116, v115
	v_mov_b32_e32 v125, v118
	v_add_f32_e32 v1, 1.0, v1
	v_rcp_f32_e32 v115, v1
	v_add_f32_e32 v1, 1.0, v116
	v_rcp_f32_e32 v123, v1
	v_mov_b32_e32 v118, v117
	v_pk_mul_f32 v[110:111], v[118:119], v[110:111]
	v_pk_mul_f32 v[112:113], v[124:125], v[112:113]
	v_pk_mul_f32 v[110:111], v[122:123], v[110:111]
	v_pk_mul_f32 v[112:113], v[114:115], v[112:113]
	v_bfe_u32 v1, v111, 16, 1
	v_bfe_u32 v114, v110, 16, 1
	v_bfe_u32 v115, v109, 16, 1
	v_bfe_u32 v116, v108, 16, 1
	v_add3_u32 v108, v108, v116, s94
	v_add3_u32 v109, v109, v115, s94
	v_add3_u32 v110, v110, v114, s94
	v_add3_u32 v1, v111, v1, s94
	v_bfe_u32 v111, v120, 16, 1
	v_bfe_u32 v114, v121, 16, 1
	v_bfe_u32 v115, v112, 16, 1
	v_bfe_u32 v116, v113, 16, 1
	v_add3_u32 v113, v113, v116, s94
	v_add3_u32 v112, v112, v115, s94
	v_add3_u32 v114, v121, v114, s94
	v_add3_u32 v111, v120, v111, s94
	v_lshrrev_b32_e32 v115, 16, v111
	v_lshrrev_b32_e32 v114, 16, v114
	v_lshrrev_b32_e32 v112, 16, v112
	v_lshrrev_b32_e32 v111, 16, v113
	v_and_or_b32 v111, v1, s93, v111
	v_and_or_b32 v110, v110, s93, v112
	v_and_or_b32 v109, v109, s93, v114
	v_and_or_b32 v108, v108, s93, v115
	v_pk_fma_f32 v[2:3], v[130:131], v[224:225], v[226:227]
	global_store_dwordx4 v[164:165], v[108:111], off
	v_lshl_add_u64 v[164:165], v[164:165], 0, s[76:77]
	s_cbranch_scc0 .LBB0_229
